# small-item attention queue (SWA blocks, meta rows): the next queue index is fetched while the current item runs
# baseline (speedup 1.0000x reference)
; __device__ __forceinline__ int ltid() { return launder((int)threadIdx.x); }
; __device__ __forceinline__ void attn_phase(const Params& P, int layer) {
;     ...
;   for (;;) {
;     __syncthreads();
;     if (ltid() == 0) *slot = (int)atomicAdd(ctl + 32 + layer, 1u);
;     __syncthreads();
;     const int idx = __builtin_amdgcn_readfirstlane(*slot);
.LBB0_1325:
	v_cmp_eq_u32_e32 vcc, 0, v155
	s_and_saveexec_b64 s[2:3], vcc
	v_mov_b32_e32 v250, 1
	s_nop 0
	global_atomic_add v250, v1, v250, s[52:53] offset:128 sc0
	s_or_b64 exec, exec, s[2:3]
	v_readlane_b32 s0, v254, 54
	s_mul_i32 s0, s0, 6
	v_readlane_b32 s1, v254, 55
	s_branch .LBB0_1328

; __device__ __forceinline__ int ltid() { return launder((int)threadIdx.x); }
; __device__ __forceinline__ void attn_phase(const Params& P, int layer) {
;     ...
;   for (;;) {
;     __syncthreads();
;     if (ltid() == 0) *slot = (int)atomicAdd(ctl + 32 + layer, 1u);
;     __syncthreads();
;     const int idx = __builtin_amdgcn_readfirstlane(*slot);
;     if (idx >= N_SMALL) break;
.LBB0_1328:
	s_waitcnt lgkmcnt(0)
	v_mov_b32_e32 v0, v155
	s_barrier
	s_nop 0
	v_cmp_eq_u32_e32 vcc, 0, v0
	s_and_saveexec_b64 s[2:3], vcc
	s_cbranch_execz .LBB0_1332
	s_mov_b64 s[6:7], exec
	v_mbcnt_lo_u32_b32 v0, s6, 0
	v_mbcnt_hi_u32_b32 v0, s7, v0
	v_cmp_eq_u32_e32 vcc, 0, v0
	s_and_saveexec_b64 s[4:5], vcc
	s_cbranch_execz .LBB0_1331
	s_waitcnt vmcnt(0)
	v_mov_b32_e32 v2, v250
	v_mov_b32_e32 v250, 1
	s_nop 0
	global_atomic_add v250, v1, v250, s[52:53] offset:128 sc0
.LBB0_1331:
	s_or_b64 exec, exec, s[4:5]
	v_readfirstlane_b32 s1, v2
	v_mov_b32_e32 v2, s51
	s_nop 0
	v_add_u32_e32 v0, s1, v0
	ds_write_b32 v2, v0
